# barrier release: the XCD leader stores the new generation value (plain store, stays in the XCD L2) instead of an atomic add that drops the polled line from L2
# speedup vs baseline: 1.0083x; 1.0083x over previous
.Lbar_local:
	s_waitcnt vmcnt(0) lgkmcnt(0)
	v_add_u32_e32 v2, 1, v3
	v_readlane_b32 s4, v253, 8
	v_readlane_b32 s5, v253, 9
	s_nop 4
	global_store_dword v131, v2, s[4:5]
	buffer_inv sc1
	s_waitcnt vmcnt(0)
	s_branch .LBB0_61
.Lbar_global:
	v_mov_b32_e32 v9, v3
	s_mov_b64 s[4:5], exec
	buffer_wbl2 sc1
	s_waitcnt lgkmcnt(0)
	s_waitcnt vmcnt(0)
	buffer_inv sc1
	v_mbcnt_lo_u32_b32 v3, s4, 0
	v_mbcnt_hi_u32_b32 v3, s5, v3
	v_cmp_eq_u32_e32 vcc, 0, v3
	s_and_saveexec_b64 s[6:7], vcc
	s_cbranch_execz .LBB0_44
	s_bcnt1_i32_b64 s4, s[4:5]
	v_mov_b32_e32 v4, s4
	v_readlane_b32 s4, v253, 10
	v_readlane_b32 s5, v253, 11
	s_nop 4
	global_atomic_add v4, v131, v4, s[4:5] sc0

.LBB0_58:
	s_or_b64 exec, exec, s[4:5]
	s_mov_b64 s[4:5], exec
	v_mbcnt_lo_u32_b32 v2, s4, 0
	v_mbcnt_hi_u32_b32 v2, s5, v2
	v_cmp_eq_u32_e32 vcc, 0, v2
	s_waitcnt vmcnt(0)
	s_and_saveexec_b64 s[6:7], vcc
	s_cbranch_execz .LBB0_60
	v_add_u32_e32 v2, 1, v9
	v_readlane_b32 s4, v253, 8
	v_readlane_b32 s5, v253, 9
	s_nop 4
	global_store_dword v131, v2, s[4:5]
